# initial software grid sync removed (XCD barrier census completes itself); on top of scan burst schedule etc.
# speedup vs baseline: 1.0162x; 1.0026x over previous
.LBB0_6:
	s_or_b64 exec, exec, s[2:3]
	v_lshrrev_b32_e32 v1, 20, v0
	v_lshrrev_b32_e32 v0, 10, v0
	v_or_b32_e32 v0, v0, v1
	s_movk_i32 s2, 0x3ff
	v_and_or_b32 v0, v0, s2, v210
	v_cmp_eq_u32_e32 vcc, 0, v0
	s_barrier
	s_and_saveexec_b64 s[2:3], vcc
.LBB0_16:
	s_or_b64 exec, exec, s[2:3]
	s_add_i32 s85, 0, 0x20200
	s_barrier
